# ClusterFinish L1 invalidate moved from after the poll to arrive time (8 split seams)
# speedup vs baseline: 1.0153x; 1.0153x over previous
.LBB0_110:
	s_andn2_b64 vcc, exec, s[14:15]
	s_cbranch_vccz .LBB0_112
	v_mov_b32_e32 v7, 0
	v_mov_b32_e32 v8, 1
	global_store_dword v7, v8, s[0:1] sc1
.LBB0_112:
	s_waitcnt vmcnt(0)
	s_waitcnt vmcnt(0)
.LBB0_113:
	s_or_b64 exec, exec, s[6:7]
	s_lshr_b32 s0, s28, 3
	s_lshl_b32 s0, s0, 3
	s_sub_i32 s0, s27, s0
	s_lshl_b32 s1, s26, 3
	s_sext_i32_i8 s0, s0
	s_add_i32 s51, s1, s0
	s_lshl_b32 s52, s51, 19
	s_add_u32 s12, s2, 0x3000000
	s_addc_u32 s0, s3, 0
	v_lshl_add_u32 v156, v3, 11, v4
	s_and_b32 s13, s0, 0xffff
	s_mov_b32 s15, 0x20000
	s_mov_b32 s14, -1
	s_barrier
	s_mov_b32 m0, s21
	s_nop 0
	buffer_load_dwordx4 v156, s[12:15], s52 offen lds
	v_lshl_add_u32 v157, v5, 11, v6
	s_add_i32 s27, s21, 0x2000
	s_mov_b32 m0, s27
	s_nop 0
	buffer_load_dwordx4 v157, s[12:15], s52 offen lds
	s_add_i32 s28, s21, 0x4000
	s_or_b32 s5, s52, 0x40000
	s_mov_b32 m0, s28
	s_nop 0
	buffer_load_dwordx4 v156, s[12:15], s5 offen lds
	s_ashr_i32 s4, s41, 8
	s_add_i32 s30, s21, 0x6000
	s_mov_b32 m0, s30
	s_nop 0
	buffer_load_dwordx4 v157, s[12:15], s5 offen lds
	s_cmp_eq_u32 s4, 1
	s_mov_b32 s26, 0
	s_mov_b32 s29, 0x40000
	s_cselect_b64 s[0:1], -1, 0
	s_cmp_lg_u32 s4, 1
	s_cbranch_scc1 .LBB0_115
	s_barrier

.LBB0_209:
	s_andn2_b64 vcc, exec, s[12:13]
	s_cbranch_vccz .LBB0_211
	v_mov_b32_e32 v2, 0
	v_mov_b32_e32 v3, 1
	global_store_dword v2, v3, s[20:21] sc1
.LBB0_211:
	s_waitcnt vmcnt(0)
	s_waitcnt vmcnt(0)
.LBB0_212:
	s_or_b64 exec, exec, s[4:5]
	s_lshr_b32 s3, s29, 3
	s_lshl_b32 s3, s3, 3
	s_ashr_i32 s2, s28, 5
	s_sub_i32 s3, s24, s3
	s_lshl_b32 s2, s2, 3
	s_sext_i32_i8 s3, s3
	s_add_i32 s29, s2, s3
	s_lshl_b32 s39, s29, 19
	s_add_u32 s12, s16, 0xa800000
	s_addc_u32 s2, s17, 0
	s_and_b32 s13, s2, 0xffff
	s_mov_b32 s15, 0x20000
	s_mov_b32 s14, -1
	s_barrier
	s_mov_b32 m0, s31
	s_nop 0
	buffer_load_dwordx4 v130, s[12:15], s39 offen lds
	s_add_i32 s40, s31, 0x2000
	s_mov_b32 m0, s40
	s_nop 0
	buffer_load_dwordx4 v131, s[12:15], s39 offen lds
	s_add_i32 s41, s31, 0x4000
	s_or_b32 s2, s39, 0x40000
	s_mov_b32 m0, s41
	s_nop 0
	buffer_load_dwordx4 v130, s[12:15], s2 offen lds
	s_add_i32 s42, s31, 0x6000
	s_mov_b32 m0, s42
	s_nop 0
	buffer_load_dwordx4 v131, s[12:15], s2 offen lds
	s_ashr_i32 s24, s27, 8
	s_cmp_lg_u32 s24, 1
	s_cbranch_scc1 .LBB0_214
	s_barrier

.LBB0_313:
	s_mov_b64 s[4:5], exec
	v_mbcnt_lo_u32_b32 v2, s4, 0
	v_mbcnt_hi_u32_b32 v2, s5, v2
	v_cmp_eq_u32_e32 vcc, 0, v2
	s_and_b64 s[8:9], exec, vcc
	s_mov_b64 exec, s[8:9]
	s_cbranch_execz .LBB0_315
	s_bcnt1_i32_b64 s4, s[4:5]
	s_lshl_b32 s5, s6, 3
	s_and_b32 s5, s5, 56
	s_bfe_u32 s6, s6, 0x30003
	s_or_b32 s5, s5, s6
	s_lshl_b32 s5, s5, 8
	s_waitcnt lgkmcnt(0)
	s_add_u32 s2, s2, s5
	s_addc_u32 s3, s3, 0
	v_mov_b32_e32 v2, 0x1028000
	v_mov_b32_e32 v3, s4
	global_atomic_add v2, v3, s[2:3]
	buffer_inv sc1

.LBB0_342:
	s_andn2_b64 vcc, exec, s[12:13]
	s_cbranch_vccz .LBB0_344
	v_mov_b32_e32 v7, 0
	v_mov_b32_e32 v8, 1
	global_store_dword v7, v8, s[0:1] sc1
.LBB0_344:
	s_waitcnt vmcnt(0)
	s_waitcnt vmcnt(0)
.LBB0_345:
	s_or_b64 exec, exec, s[4:5]
	s_lshr_b32 s0, s22, 3
	s_lshl_b32 s0, s0, 3
	s_sub_i32 s0, s21, s0
	s_lshl_b32 s1, s20, 3
	s_sext_i32_i16 s0, s0
	s_add_i32 s61, s1, s0
	s_lshl_b32 s63, s61, 19
	s_add_u32 s12, s16, 0xa800000
	s_addc_u32 s1, s17, 0
	v_lshl_add_u32 v147, v3, 10, v4
	s_and_b32 s13, s1, 0xffff
	s_mov_b32 s15, 0x20000
	s_mov_b32 s14, -1
	s_barrier
	s_mov_b32 m0, s33
	s_nop 0
	buffer_load_dwordx4 v147, s[12:15], s63 offen lds
	v_lshl_add_u32 v148, v5, 10, v6
	s_add_i32 s2, s33, 0x2000
	s_mov_b32 m0, s2
	s_nop 0
	buffer_load_dwordx4 v148, s[12:15], s63 offen lds
	s_add_i32 s3, s33, 0x4000
	s_or_b32 s1, s63, 0x20000
	s_mov_b32 m0, s3
	s_nop 0
	buffer_load_dwordx4 v147, s[12:15], s1 offen lds
	s_ashr_i32 s0, s24, 8
	s_add_i32 s38, s33, 0x6000
	s_mov_b32 m0, s38
	s_nop 0
	buffer_load_dwordx4 v148, s[12:15], s1 offen lds
	s_cmp_eq_u32 s0, 1
	s_mov_b32 s58, 0
	s_cselect_b64 s[6:7], -1, 0
	s_cmp_lg_u32 s0, 1
	s_cbranch_scc1 .LBB0_347
	s_barrier

.LBB0_449:
	s_andn2_b64 vcc, exec, s[6:7]
	s_cbranch_vccz .LBB0_451
	v_mov_b32_e32 v2, 0
	v_mov_b32_e32 v3, 1
	global_store_dword v2, v3, s[20:21] sc1
.LBB0_451:
	s_waitcnt vmcnt(0)
	s_waitcnt vmcnt(0)
.LBB0_452:
	s_or_b64 exec, exec, s[2:3]
	s_add_u32 s12, s16, 0x5000000
	s_addc_u32 s0, s17, 0
	s_mul_i32 s3, s31, 0x160000
	s_and_b32 s13, s0, 0xffff
	s_mov_b32 s15, 0x20000
	s_mov_b32 s14, -1
	s_barrier
	s_mov_b32 m0, s28
	s_nop 0
	buffer_load_dwordx4 v130, s[12:15], s3 offen lds
	s_add_i32 s37, s28, 0x2000
	s_mov_b32 m0, s37
	s_nop 0
	buffer_load_dwordx4 v131, s[12:15], s3 offen lds
	s_add_i32 s38, s28, 0x4000
	s_add_i32 s0, s3, 0xb0000
	s_mov_b32 m0, s38
	s_nop 0
	buffer_load_dwordx4 v130, s[12:15], s0 offen lds
	s_add_i32 s39, s28, 0x6000
	s_mov_b32 m0, s39
	s_nop 0
	buffer_load_dwordx4 v131, s[12:15], s0 offen lds
	s_ashr_i32 s24, s27, 8
	s_cmp_lg_u32 s24, 1
	s_cbranch_scc1 .LBB0_454
	s_barrier

.LBB0_606:
	s_andn2_b64 vcc, exec, s[8:9]
	s_cbranch_vccz .LBB0_608
	v_mov_b32_e32 v7, 0
	v_mov_b32_e32 v8, 1
	global_store_dword v7, v8, s[0:1] sc1
.LBB0_608:
	s_waitcnt vmcnt(0)
	s_waitcnt vmcnt(0)
.LBB0_609:
	s_or_b64 exec, exec, s[4:5]
	s_add_u32 s16, s20, 0x5000000
	s_addc_u32 s1, s21, 0
	s_mul_i32 s2, s40, 0x160000
	v_lshl_add_u32 v206, v3, 10, v4
	s_and_b32 s17, s1, 0xffff
	s_mov_b32 s19, 0x20000
	s_mov_b32 s18, -1
	s_barrier
	s_mov_b32 m0, s47
	s_nop 0
	buffer_load_dwordx4 v206, s[16:19], s2 offen lds
	v_lshl_add_u32 v207, v5, 10, v6
	s_add_i32 s52, s47, 0x2000
	s_mov_b32 m0, s52
	s_nop 0
	buffer_load_dwordx4 v207, s[16:19], s2 offen lds
	s_add_i32 s53, s47, 0x4000
	s_add_i32 s1, s2, 0x20000
	s_mov_b32 m0, s53
	s_nop 0
	buffer_load_dwordx4 v206, s[16:19], s1 offen lds
	s_ashr_i32 s0, s36, 8
	s_add_i32 s54, s47, 0x6000
	s_mov_b32 m0, s54
	s_nop 0
	buffer_load_dwordx4 v207, s[16:19], s1 offen lds
	s_cmp_eq_u32 s0, 1
	s_mov_b32 s80, s73
	s_mov_b32 s77, s72
	s_mov_b32 s11, 0
	s_cselect_b64 s[24:25], -1, 0
	s_cmp_lg_u32 s0, 1
	s_cbranch_scc1 .LBB0_611
	s_barrier

.LBB0_929:
	s_andn2_b64 vcc, exec, s[6:7]
	s_cbranch_vccz .LBB0_931
	v_mov_b32_e32 v2, 0
	v_mov_b32_e32 v3, 1
	global_store_dword v2, v3, s[20:21] sc1
.LBB0_931:
	s_waitcnt vmcnt(0)
	s_waitcnt vmcnt(0)
.LBB0_932:
	s_or_b64 exec, exec, s[2:3]
	s_lshr_b32 s1, s30, 3
	s_lshl_b32 s1, s1, 3
	s_ashr_i32 s0, s15, 5
	s_sub_i32 s1, s14, s1
	s_lshl_b32 s0, s0, 3
	s_sext_i32_i8 s1, s1
	s_add_i32 s31, s0, s1
	s_lshl_b32 s37, s31, 19
	s_add_u32 s12, s16, 0xdc00000
	s_addc_u32 s0, s17, 0
	s_and_b32 s13, s0, 0xffff
	s_mov_b32 s15, 0x20000
	s_mov_b32 s14, -1
	s_barrier
	s_mov_b32 m0, s28
	s_nop 0
	buffer_load_dwordx4 v6, s[12:15], s37 offen lds
	s_add_i32 s38, s28, 0x2000
	s_mov_b32 m0, s38
	s_nop 0
	buffer_load_dwordx4 v7, s[12:15], s37 offen lds
	s_add_i32 s40, s28, 0x4000
	s_or_b32 s0, s37, 0x20000
	s_mov_b32 m0, s40
	s_nop 0
	buffer_load_dwordx4 v6, s[12:15], s0 offen lds
	s_add_i32 s41, s28, 0x6000
	s_mov_b32 m0, s41
	s_nop 0
	buffer_load_dwordx4 v7, s[12:15], s0 offen lds
	s_ashr_i32 s2, s26, 8
	s_mov_b32 s39, 0
	s_cmp_lg_u32 s2, 1
	s_cbranch_scc1 .LBB0_934
	s_barrier

.LBB0_1061:
	s_andn2_b64 vcc, exec, s[14:15]
	s_cbranch_vccz .LBB0_1063
	v_mov_b32_e32 v7, 0
	v_mov_b32_e32 v8, 1
	global_store_dword v7, v8, s[2:3] sc1
.LBB0_1063:
	s_waitcnt vmcnt(0)
	s_waitcnt vmcnt(0)
.LBB0_1064:
	s_or_b64 exec, exec, s[6:7]
	s_lshr_b32 s2, s22, 3
	s_lshl_b32 s2, s2, 3
	s_sub_i32 s2, s19, s2
	s_lshl_b32 s3, s18, 3
	s_sext_i32_i16 s2, s2
	s_add_i32 s53, s3, s2
	s_lshl_b32 s55, s53, 19
	s_add_u32 s12, s0, 0xa800000
	s_addc_u32 s2, s1, 0
	v_lshl_add_u32 v146, v3, 10, v4
	s_and_b32 s13, s2, 0xffff
	s_mov_b32 s15, 0x20000
	s_mov_b32 s14, -1
	s_barrier
	s_mov_b32 m0, s26
	s_nop 0
	buffer_load_dwordx4 v146, s[12:15], s55 offen lds
	v_lshl_add_u32 v147, v5, 10, v6
	s_add_i32 s2, s26, 0x2000
	s_mov_b32 m0, s2
	s_nop 0
	buffer_load_dwordx4 v147, s[12:15], s55 offen lds
	s_add_i32 s3, s26, 0x4000
	s_or_b32 s5, s55, 0x20000
	s_mov_b32 m0, s3
	s_nop 0
	buffer_load_dwordx4 v146, s[12:15], s5 offen lds
	s_ashr_i32 s4, s20, 8
	s_add_i32 s31, s26, 0x6000
	s_mov_b32 m0, s31
	s_nop 0
	buffer_load_dwordx4 v147, s[12:15], s5 offen lds
	s_cmp_eq_u32 s4, 1
	s_mov_b32 s50, 0
	s_cselect_b64 s[6:7], -1, 0
	s_cmp_lg_u32 s4, 1
	s_cbranch_scc1 .LBB0_1066
	s_barrier

.LBB0_1119:
	s_waitcnt vmcnt(0) lgkmcnt(0)
	s_waitcnt vmcnt(0)
